# k24 + packed f32 (v_pk_mul/v_pk_add) for the batched sigmoid chains of the G1 forget-gate epilogue (instruction selection in a VALU-bound epilogue)
# speedup vs baseline: 1.0076x; 1.0039x over previous
; __device__ __forceinline__ unsigned pkh2(float lo, float hi) { _Float16 a = (_Float16)lo, b = (_Float16)hi; return (unsigned)__builtin_bit_cast(unsigned short, a) | ((unsigned)__builtin_bit_cast(unsigned short, b) << 16); }
;     template <int NA, int NM> __device__ __forceinline__ void operator()(const f32x4 (&acc)[NA][2][NM][2], const pg8::Unit& u, int ro, int wr, int wc, int fr, int fq) const {
;     ...
;                         c0.x = __builtin_amdgcn_rcpf(1.0f + __builtin_amdgcn_exp2f(v0.x * 1.4426950408889634f)); c0.y = __builtin_amdgcn_rcpf(1.0f + __builtin_amdgcn_exp2f(v0.y * 1.4426950408889634f));
;                         c0.z = __builtin_amdgcn_rcpf(1.0f + __builtin_amdgcn_exp2f(v0.z * 1.4426950408889634f)); c0.w = __builtin_amdgcn_rcpf(1.0f + __builtin_amdgcn_exp2f(v0.w * 1.4426950408889634f));
;                         c1.x = __builtin_amdgcn_rcpf(1.0f + __builtin_amdgcn_exp2f(v1.x * 1.4426950408889634f)); c1.y = __builtin_amdgcn_rcpf(1.0f + __builtin_amdgcn_exp2f(v1.y * 1.4426950408889634f));
;                         c1.z = __builtin_amdgcn_rcpf(1.0f + __builtin_amdgcn_exp2f(v1.z * 1.4426950408889634f)); c1.w = __builtin_amdgcn_rcpf(1.0f + __builtin_amdgcn_exp2f(v1.w * 1.4426950408889634f));
;                         w.x = pkh2(c0.x, c0.y); w.y = pkh2(c0.z, c0.w); w.z = pkh2(c1.x, c1.y); w.w = pkh2(c1.z, c1.w);
;                         unsigned short* dst = (type == 1 ? Ff : Fb) + (size_t)row * D + (c - type * 1024);
;                         *(u32x4*)dst = w;
.LBB0_419:
	s_lshl_b32 s7, s7, 10
	v_lshlrev_b64 v[176:177], 11, v[176:177]
	s_andn2_b64 vcc, exec, s[66:67]
	v_subrev_u32_e32 v143, s7, v156
	s_cbranch_vccnz .LBB0_421
	s_mov_b32 s100, 0x3fb8aa3b
	v_pk_mul_f32 v[138:139], v[174:175], s[100:101] op_sel_hi:[1,0]
	v_pk_mul_f32 v[140:141], v[172:173], s[100:101] op_sel_hi:[1,0]
	v_mul_f32_e32 v159, 0x3fb8aa3b, v170
	v_mul_f32_e32 v162, 0x3fb8aa3b, v171
	v_pk_mul_f32 v[160:161], v[160:161], s[100:101] op_sel_hi:[1,0]
	v_exp_f32_e32 v138, v138
	v_exp_f32_e32 v139, v139
	v_exp_f32_e32 v140, v140
	v_exp_f32_e32 v141, v141
	v_exp_f32_e32 v159, v159
	v_exp_f32_e32 v162, v162
	v_exp_f32_e32 v160, v160
	v_exp_f32_e32 v161, v161
	v_pk_add_f32 v[138:139], v[138:139], 1.0 op_sel_hi:[1,0]
	v_pk_add_f32 v[140:141], v[140:141], 1.0 op_sel_hi:[1,0]
	v_add_f32_e32 v159, 1.0, v159
	v_add_f32_e32 v162, 1.0, v162
	v_pk_add_f32 v[160:161], v[160:161], 1.0 op_sel_hi:[1,0]
	v_rcp_f32_e32 v138, v138
	v_rcp_f32_e32 v139, v139
	v_rcp_f32_e32 v140, v140
	v_rcp_f32_e32 v141, v141
	v_rcp_f32_e32 v159, v159
	v_rcp_f32_e32 v162, v162
	v_rcp_f32_e32 v160, v160
	v_rcp_f32_e32 v161, v161
	v_cvt_f16_f32_e32 v138, v138
	v_cvt_f16_f32_sdwa v139, v139 dst_sel:WORD_1 dst_unused:UNUSED_PAD src0_sel:DWORD
	v_cvt_f16_f32_e32 v140, v140
	v_cvt_f16_f32_sdwa v141, v141 dst_sel:WORD_1 dst_unused:UNUSED_PAD src0_sel:DWORD
	v_cvt_f16_f32_e32 v159, v159
	v_cvt_f16_f32_sdwa v162, v162 dst_sel:WORD_1 dst_unused:UNUSED_PAD src0_sel:DWORD
	v_cvt_f16_f32_e32 v160, v160
	v_cvt_f16_f32_sdwa v161, v161 dst_sel:WORD_1 dst_unused:UNUSED_PAD src0_sel:DWORD
	s_and_b64 s[10:11], s[68:69], exec
	s_cselect_b32 s11, s61, s23
	s_cselect_b32 s10, s60, s22
	v_or_b32_e32 v138, v139, v138
	v_or_b32_e32 v139, v141, v140
	v_or_b32_e32 v140, v162, v159
	v_or_b32_e32 v141, v161, v160
	v_lshl_add_u64 v[180:181], s[10:11], 0, v[176:177]
	v_subrev_u32_e32 v182, s7, v156

; __device__ __forceinline__ unsigned pkh2(float lo, float hi) { _Float16 a = (_Float16)lo, b = (_Float16)hi; return (unsigned)__builtin_bit_cast(unsigned short, a) | ((unsigned)__builtin_bit_cast(unsigned short, b) << 16); }
;     template <int NA, int NM> __device__ __forceinline__ void operator()(const f32x4 (&acc)[NA][2][NM][2], const pg8::Unit& u, int ro, int wr, int wc, int fr, int fq) const {
;     ...
;                         c0.x = __builtin_amdgcn_rcpf(1.0f + __builtin_amdgcn_exp2f(v0.x * 1.4426950408889634f)); c0.y = __builtin_amdgcn_rcpf(1.0f + __builtin_amdgcn_exp2f(v0.y * 1.4426950408889634f));
;                         c0.z = __builtin_amdgcn_rcpf(1.0f + __builtin_amdgcn_exp2f(v0.z * 1.4426950408889634f)); c0.w = __builtin_amdgcn_rcpf(1.0f + __builtin_amdgcn_exp2f(v0.w * 1.4426950408889634f));
;                         c1.x = __builtin_amdgcn_rcpf(1.0f + __builtin_amdgcn_exp2f(v1.x * 1.4426950408889634f)); c1.y = __builtin_amdgcn_rcpf(1.0f + __builtin_amdgcn_exp2f(v1.y * 1.4426950408889634f));
;                         c1.z = __builtin_amdgcn_rcpf(1.0f + __builtin_amdgcn_exp2f(v1.z * 1.4426950408889634f)); c1.w = __builtin_amdgcn_rcpf(1.0f + __builtin_amdgcn_exp2f(v1.w * 1.4426950408889634f));
;                         w.x = pkh2(c0.x, c0.y); w.y = pkh2(c0.z, c0.w); w.z = pkh2(c1.x, c1.y); w.w = pkh2(c1.z, c1.w);
;                         unsigned short* dst = (type == 1 ? Ff : Fb) + (size_t)row * D + (c - type * 1024);
;                         *(u32x4*)dst = w;
.LBB0_423:
	s_andn2_b64 vcc, exec, s[72:73]
	v_subrev_u32_e32 v135, s7, v172
	s_cbranch_vccnz .LBB0_425
	s_mov_b32 s100, 0x3fb8aa3b
	v_pk_mul_f32 v[130:131], v[160:161], s[100:101] op_sel_hi:[1,0]
	v_pk_mul_f32 v[132:133], v[140:141], s[100:101] op_sel_hi:[1,0]
	v_pk_mul_f32 v[138:139], v[138:139], s[100:101] op_sel_hi:[1,0]
	v_pk_mul_f32 v[136:137], v[136:137], s[100:101] op_sel_hi:[1,0]
	v_exp_f32_e32 v130, v130
	v_exp_f32_e32 v131, v131
	v_exp_f32_e32 v132, v132
	v_exp_f32_e32 v133, v133
	v_exp_f32_e32 v138, v138
	v_exp_f32_e32 v139, v139
	v_exp_f32_e32 v136, v136
	v_exp_f32_e32 v137, v137
	v_pk_add_f32 v[130:131], v[130:131], 1.0 op_sel_hi:[1,0]
	v_pk_add_f32 v[132:133], v[132:133], 1.0 op_sel_hi:[1,0]
	v_pk_add_f32 v[138:139], v[138:139], 1.0 op_sel_hi:[1,0]
	v_pk_add_f32 v[136:137], v[136:137], 1.0 op_sel_hi:[1,0]
	v_rcp_f32_e32 v130, v130
	v_rcp_f32_e32 v131, v131
	v_rcp_f32_e32 v132, v132
	v_rcp_f32_e32 v133, v133
	v_rcp_f32_e32 v138, v138
	v_rcp_f32_e32 v139, v139
	v_rcp_f32_e32 v136, v136
	v_rcp_f32_e32 v137, v137
	v_cvt_f16_f32_e32 v130, v130
	v_cvt_f16_f32_sdwa v131, v131 dst_sel:WORD_1 dst_unused:UNUSED_PAD src0_sel:DWORD
	v_cvt_f16_f32_e32 v132, v132
	v_cvt_f16_f32_sdwa v133, v133 dst_sel:WORD_1 dst_unused:UNUSED_PAD src0_sel:DWORD
	v_cvt_f16_f32_e32 v138, v138
	v_cvt_f16_f32_sdwa v139, v139 dst_sel:WORD_1 dst_unused:UNUSED_PAD src0_sel:DWORD
	v_cvt_f16_f32_e32 v136, v136
	v_cvt_f16_f32_sdwa v137, v137 dst_sel:WORD_1 dst_unused:UNUSED_PAD src0_sel:DWORD
	s_and_b64 s[10:11], s[68:69], exec
	s_cselect_b32 s11, s61, s23
	s_cselect_b32 s10, s60, s22
	v_or_b32_e32 v130, v131, v130
	v_or_b32_e32 v131, v133, v132
	v_or_b32_e32 v132, v139, v138
	v_or_b32_e32 v133, v137, v136
	v_lshl_add_u64 v[144:145], s[10:11], 0, v[176:177]
	v_subrev_u32_e32 v158, s7, v172

; __device__ __forceinline__ unsigned pkh2(float lo, float hi) { _Float16 a = (_Float16)lo, b = (_Float16)hi; return (unsigned)__builtin_bit_cast(unsigned short, a) | ((unsigned)__builtin_bit_cast(unsigned short, b) << 16); }
;     template <int NA, int NM> __device__ __forceinline__ void operator()(const f32x4 (&acc)[NA][2][NM][2], const pg8::Unit& u, int ro, int wr, int wc, int fr, int fq) const {
;     ...
;                         c0.x = __builtin_amdgcn_rcpf(1.0f + __builtin_amdgcn_exp2f(v0.x * 1.4426950408889634f)); c0.y = __builtin_amdgcn_rcpf(1.0f + __builtin_amdgcn_exp2f(v0.y * 1.4426950408889634f));
;                         c0.z = __builtin_amdgcn_rcpf(1.0f + __builtin_amdgcn_exp2f(v0.z * 1.4426950408889634f)); c0.w = __builtin_amdgcn_rcpf(1.0f + __builtin_amdgcn_exp2f(v0.w * 1.4426950408889634f));
;                         c1.x = __builtin_amdgcn_rcpf(1.0f + __builtin_amdgcn_exp2f(v1.x * 1.4426950408889634f)); c1.y = __builtin_amdgcn_rcpf(1.0f + __builtin_amdgcn_exp2f(v1.y * 1.4426950408889634f));
;                         c1.z = __builtin_amdgcn_rcpf(1.0f + __builtin_amdgcn_exp2f(v1.z * 1.4426950408889634f)); c1.w = __builtin_amdgcn_rcpf(1.0f + __builtin_amdgcn_exp2f(v1.w * 1.4426950408889634f));
;                         w.x = pkh2(c0.x, c0.y); w.y = pkh2(c0.z, c0.w); w.z = pkh2(c1.x, c1.y); w.w = pkh2(c1.z, c1.w);
;                         unsigned short* dst = (type == 1 ? Ff : Fb) + (size_t)row * D + (c - type * 1024);
;                         *(u32x4*)dst = w;
.LBB0_427:
	s_andn2_b64 vcc, exec, s[70:71]
	v_lshlrev_b64 v[126:127], 11, v[140:141]
	s_cbranch_vccnz .LBB0_429
	s_mov_b32 s100, 0x3fb8aa3b
	v_pk_mul_f32 v[122:123], v[144:145], s[100:101] op_sel_hi:[1,0]
	v_pk_mul_f32 v[124:125], v[138:139], s[100:101] op_sel_hi:[1,0]
	v_pk_mul_f32 v[132:133], v[132:133], s[100:101] op_sel_hi:[1,0]
	v_pk_mul_f32 v[130:131], v[130:131], s[100:101] op_sel_hi:[1,0]
	v_exp_f32_e32 v122, v122
	v_exp_f32_e32 v123, v123
	v_exp_f32_e32 v124, v124
	v_exp_f32_e32 v125, v125
	v_exp_f32_e32 v132, v132
	v_exp_f32_e32 v133, v133
	v_exp_f32_e32 v130, v130
	v_exp_f32_e32 v131, v131
	v_pk_add_f32 v[122:123], v[122:123], 1.0 op_sel_hi:[1,0]
	v_pk_add_f32 v[124:125], v[124:125], 1.0 op_sel_hi:[1,0]
	v_pk_add_f32 v[132:133], v[132:133], 1.0 op_sel_hi:[1,0]
	v_pk_add_f32 v[130:131], v[130:131], 1.0 op_sel_hi:[1,0]
	v_rcp_f32_e32 v122, v122
	v_rcp_f32_e32 v123, v123
	v_rcp_f32_e32 v124, v124
	v_rcp_f32_e32 v125, v125
	v_rcp_f32_e32 v132, v132
	v_rcp_f32_e32 v133, v133
	v_rcp_f32_e32 v130, v130
	v_rcp_f32_e32 v131, v131
	v_cvt_f16_f32_e32 v122, v122
	v_cvt_f16_f32_sdwa v123, v123 dst_sel:WORD_1 dst_unused:UNUSED_PAD src0_sel:DWORD
	v_cvt_f16_f32_e32 v124, v124
	v_cvt_f16_f32_sdwa v125, v125 dst_sel:WORD_1 dst_unused:UNUSED_PAD src0_sel:DWORD
	v_cvt_f16_f32_e32 v132, v132
	v_cvt_f16_f32_sdwa v133, v133 dst_sel:WORD_1 dst_unused:UNUSED_PAD src0_sel:DWORD
	v_cvt_f16_f32_e32 v130, v130
	v_cvt_f16_f32_sdwa v131, v131 dst_sel:WORD_1 dst_unused:UNUSED_PAD src0_sel:DWORD
	s_and_b64 s[10:11], s[68:69], exec
	s_cselect_b32 s11, s61, s23
	s_cselect_b32 s10, s60, s22
	v_or_b32_e32 v122, v123, v122
	v_or_b32_e32 v123, v125, v124
	v_or_b32_e32 v124, v133, v132
	v_or_b32_e32 v125, v131, v130
	v_lshl_add_u64 v[158:159], s[10:11], 0, v[126:127]
	v_subrev_u32_e32 v160, s7, v156

; __device__ __forceinline__ unsigned pkh2(float lo, float hi) { _Float16 a = (_Float16)lo, b = (_Float16)hi; return (unsigned)__builtin_bit_cast(unsigned short, a) | ((unsigned)__builtin_bit_cast(unsigned short, b) << 16); }
;     template <int NA, int NM> __device__ __forceinline__ void operator()(const f32x4 (&acc)[NA][2][NM][2], const pg8::Unit& u, int ro, int wr, int wc, int fr, int fq) const {
;     ...
;                         c0.x = __builtin_amdgcn_rcpf(1.0f + __builtin_amdgcn_exp2f(v0.x * 1.4426950408889634f)); c0.y = __builtin_amdgcn_rcpf(1.0f + __builtin_amdgcn_exp2f(v0.y * 1.4426950408889634f));
;                         c0.z = __builtin_amdgcn_rcpf(1.0f + __builtin_amdgcn_exp2f(v0.z * 1.4426950408889634f)); c0.w = __builtin_amdgcn_rcpf(1.0f + __builtin_amdgcn_exp2f(v0.w * 1.4426950408889634f));
;                         c1.x = __builtin_amdgcn_rcpf(1.0f + __builtin_amdgcn_exp2f(v1.x * 1.4426950408889634f)); c1.y = __builtin_amdgcn_rcpf(1.0f + __builtin_amdgcn_exp2f(v1.y * 1.4426950408889634f));
;                         c1.z = __builtin_amdgcn_rcpf(1.0f + __builtin_amdgcn_exp2f(v1.z * 1.4426950408889634f)); c1.w = __builtin_amdgcn_rcpf(1.0f + __builtin_amdgcn_exp2f(v1.w * 1.4426950408889634f));
;                         w.x = pkh2(c0.x, c0.y); w.y = pkh2(c0.z, c0.w); w.z = pkh2(c1.x, c1.y); w.w = pkh2(c1.z, c1.w);
;                         unsigned short* dst = (type == 1 ? Ff : Fb) + (size_t)row * D + (c - type * 1024);
;                         *(u32x4*)dst = w;
.LBB0_431:
	s_andn2_b64 vcc, exec, s[70:71]
	s_cbranch_vccnz .LBB0_433
	s_mov_b32 s100, 0x3fb8aa3b
	v_pk_mul_f32 v[114:115], v[124:125], s[100:101] op_sel_hi:[1,0]
	v_pk_mul_f32 v[116:117], v[122:123], s[100:101] op_sel_hi:[1,0]
	v_pk_mul_f32 v[120:121], v[120:121], s[100:101] op_sel_hi:[1,0]
	v_pk_mul_f32 v[118:119], v[118:119], s[100:101] op_sel_hi:[1,0]
	v_exp_f32_e32 v114, v114
	v_exp_f32_e32 v115, v115
	v_exp_f32_e32 v116, v116
	v_exp_f32_e32 v117, v117
	v_exp_f32_e32 v120, v120
	v_exp_f32_e32 v121, v121
	v_exp_f32_e32 v118, v118
	v_exp_f32_e32 v119, v119
	v_pk_add_f32 v[114:115], v[114:115], 1.0 op_sel_hi:[1,0]
	v_pk_add_f32 v[116:117], v[116:117], 1.0 op_sel_hi:[1,0]
	v_pk_add_f32 v[120:121], v[120:121], 1.0 op_sel_hi:[1,0]
	v_pk_add_f32 v[118:119], v[118:119], 1.0 op_sel_hi:[1,0]
	v_rcp_f32_e32 v114, v114
	v_rcp_f32_e32 v115, v115
	v_rcp_f32_e32 v116, v116
	v_rcp_f32_e32 v117, v117
	v_rcp_f32_e32 v120, v120
	v_rcp_f32_e32 v121, v121
	v_rcp_f32_e32 v118, v118
	v_rcp_f32_e32 v119, v119
	v_cvt_f16_f32_e32 v114, v114
	v_cvt_f16_f32_sdwa v115, v115 dst_sel:WORD_1 dst_unused:UNUSED_PAD src0_sel:DWORD
	v_cvt_f16_f32_e32 v116, v116
	v_cvt_f16_f32_sdwa v117, v117 dst_sel:WORD_1 dst_unused:UNUSED_PAD src0_sel:DWORD
	v_cvt_f16_f32_e32 v120, v120
	v_cvt_f16_f32_sdwa v121, v121 dst_sel:WORD_1 dst_unused:UNUSED_PAD src0_sel:DWORD
	v_cvt_f16_f32_e32 v118, v118
	v_cvt_f16_f32_sdwa v119, v119 dst_sel:WORD_1 dst_unused:UNUSED_PAD src0_sel:DWORD
	s_and_b64 s[10:11], s[68:69], exec
	s_cselect_b32 s11, s61, s23
	s_cselect_b32 s10, s60, s22
	v_or_b32_e32 v114, v115, v114
	v_or_b32_e32 v115, v117, v116
	v_or_b32_e32 v116, v121, v120
	v_or_b32_e32 v117, v119, v118
	v_lshl_add_u64 v[128:129], s[10:11], 0, v[126:127]
	v_subrev_u32_e32 v130, s7, v172

; __device__ __forceinline__ unsigned pkh2(float lo, float hi) { _Float16 a = (_Float16)lo, b = (_Float16)hi; return (unsigned)__builtin_bit_cast(unsigned short, a) | ((unsigned)__builtin_bit_cast(unsigned short, b) << 16); }
;     template <int NA, int NM> __device__ __forceinline__ void operator()(const f32x4 (&acc)[NA][2][NM][2], const pg8::Unit& u, int ro, int wr, int wc, int fr, int fq) const {
;     ...
;                         c0.x = __builtin_amdgcn_rcpf(1.0f + __builtin_amdgcn_exp2f(v0.x * 1.4426950408889634f)); c0.y = __builtin_amdgcn_rcpf(1.0f + __builtin_amdgcn_exp2f(v0.y * 1.4426950408889634f));
;                         c0.z = __builtin_amdgcn_rcpf(1.0f + __builtin_amdgcn_exp2f(v0.z * 1.4426950408889634f)); c0.w = __builtin_amdgcn_rcpf(1.0f + __builtin_amdgcn_exp2f(v0.w * 1.4426950408889634f));
;                         c1.x = __builtin_amdgcn_rcpf(1.0f + __builtin_amdgcn_exp2f(v1.x * 1.4426950408889634f)); c1.y = __builtin_amdgcn_rcpf(1.0f + __builtin_amdgcn_exp2f(v1.y * 1.4426950408889634f));
;                         c1.z = __builtin_amdgcn_rcpf(1.0f + __builtin_amdgcn_exp2f(v1.z * 1.4426950408889634f)); c1.w = __builtin_amdgcn_rcpf(1.0f + __builtin_amdgcn_exp2f(v1.w * 1.4426950408889634f));
;                         w.x = pkh2(c0.x, c0.y); w.y = pkh2(c0.z, c0.w); w.z = pkh2(c1.x, c1.y); w.w = pkh2(c1.z, c1.w);
;                         unsigned short* dst = (type == 1 ? Ff : Fb) + (size_t)row * D + (c - type * 1024);
;                         *(u32x4*)dst = w;
.LBB0_435:
	s_andn2_b64 vcc, exec, s[70:71]
	v_lshlrev_b64 v[110:111], 11, v[122:123]
	s_cbranch_vccnz .LBB0_437
	s_mov_b32 s100, 0x3fb8aa3b
	v_pk_mul_f32 v[106:107], v[124:125], s[100:101] op_sel_hi:[1,0]
	v_pk_mul_f32 v[108:109], v[120:121], s[100:101] op_sel_hi:[1,0]
	v_pk_mul_f32 v[116:117], v[116:117], s[100:101] op_sel_hi:[1,0]
	v_pk_mul_f32 v[114:115], v[114:115], s[100:101] op_sel_hi:[1,0]
	v_exp_f32_e32 v106, v106
	v_exp_f32_e32 v107, v107
	v_exp_f32_e32 v108, v108
	v_exp_f32_e32 v109, v109
	v_exp_f32_e32 v116, v116
	v_exp_f32_e32 v117, v117
	v_exp_f32_e32 v114, v114
	v_exp_f32_e32 v115, v115
	v_pk_add_f32 v[106:107], v[106:107], 1.0 op_sel_hi:[1,0]
	v_pk_add_f32 v[108:109], v[108:109], 1.0 op_sel_hi:[1,0]
	v_pk_add_f32 v[116:117], v[116:117], 1.0 op_sel_hi:[1,0]
	v_pk_add_f32 v[114:115], v[114:115], 1.0 op_sel_hi:[1,0]
	v_rcp_f32_e32 v106, v106
	v_rcp_f32_e32 v107, v107
	v_rcp_f32_e32 v108, v108
	v_rcp_f32_e32 v109, v109
	v_rcp_f32_e32 v116, v116
	v_rcp_f32_e32 v117, v117
	v_rcp_f32_e32 v114, v114
	v_rcp_f32_e32 v115, v115
	v_cvt_f16_f32_e32 v106, v106
	v_cvt_f16_f32_sdwa v107, v107 dst_sel:WORD_1 dst_unused:UNUSED_PAD src0_sel:DWORD
	v_cvt_f16_f32_e32 v108, v108
	v_cvt_f16_f32_sdwa v109, v109 dst_sel:WORD_1 dst_unused:UNUSED_PAD src0_sel:DWORD
	v_cvt_f16_f32_e32 v116, v116
	v_cvt_f16_f32_sdwa v117, v117 dst_sel:WORD_1 dst_unused:UNUSED_PAD src0_sel:DWORD
	v_cvt_f16_f32_e32 v114, v114
	v_cvt_f16_f32_sdwa v115, v115 dst_sel:WORD_1 dst_unused:UNUSED_PAD src0_sel:DWORD
	s_and_b64 s[10:11], s[68:69], exec
	s_cselect_b32 s11, s61, s23
	s_cselect_b32 s10, s60, s22
	v_or_b32_e32 v106, v107, v106
	v_or_b32_e32 v107, v109, v108
	v_or_b32_e32 v108, v117, v116
	v_or_b32_e32 v109, v115, v114
	v_lshl_add_u64 v[126:127], s[10:11], 0, v[110:111]
	v_subrev_u32_e32 v128, s7, v156

; __device__ __forceinline__ unsigned pkh2(float lo, float hi) { _Float16 a = (_Float16)lo, b = (_Float16)hi; return (unsigned)__builtin_bit_cast(unsigned short, a) | ((unsigned)__builtin_bit_cast(unsigned short, b) << 16); }
;     template <int NA, int NM> __device__ __forceinline__ void operator()(const f32x4 (&acc)[NA][2][NM][2], const pg8::Unit& u, int ro, int wr, int wc, int fr, int fq) const {
;     ...
;                         c0.x = __builtin_amdgcn_rcpf(1.0f + __builtin_amdgcn_exp2f(v0.x * 1.4426950408889634f)); c0.y = __builtin_amdgcn_rcpf(1.0f + __builtin_amdgcn_exp2f(v0.y * 1.4426950408889634f));
;                         c0.z = __builtin_amdgcn_rcpf(1.0f + __builtin_amdgcn_exp2f(v0.z * 1.4426950408889634f)); c0.w = __builtin_amdgcn_rcpf(1.0f + __builtin_amdgcn_exp2f(v0.w * 1.4426950408889634f));
;                         c1.x = __builtin_amdgcn_rcpf(1.0f + __builtin_amdgcn_exp2f(v1.x * 1.4426950408889634f)); c1.y = __builtin_amdgcn_rcpf(1.0f + __builtin_amdgcn_exp2f(v1.y * 1.4426950408889634f));
;                         c1.z = __builtin_amdgcn_rcpf(1.0f + __builtin_amdgcn_exp2f(v1.z * 1.4426950408889634f)); c1.w = __builtin_amdgcn_rcpf(1.0f + __builtin_amdgcn_exp2f(v1.w * 1.4426950408889634f));
;                         w.x = pkh2(c0.x, c0.y); w.y = pkh2(c0.z, c0.w); w.z = pkh2(c1.x, c1.y); w.w = pkh2(c1.z, c1.w);
;                         unsigned short* dst = (type == 1 ? Ff : Fb) + (size_t)row * D + (c - type * 1024);
;                         *(u32x4*)dst = w;
.LBB0_439:
	s_andn2_b64 vcc, exec, s[70:71]
	s_cbranch_vccnz .LBB0_441
	s_mov_b32 s100, 0x3fb8aa3b
	v_pk_mul_f32 v[98:99], v[108:109], s[100:101] op_sel_hi:[1,0]
	v_pk_mul_f32 v[100:101], v[106:107], s[100:101] op_sel_hi:[1,0]
	v_pk_mul_f32 v[104:105], v[104:105], s[100:101] op_sel_hi:[1,0]
	v_pk_mul_f32 v[102:103], v[102:103], s[100:101] op_sel_hi:[1,0]
	v_exp_f32_e32 v98, v98
	v_exp_f32_e32 v99, v99
	v_exp_f32_e32 v100, v100
	v_exp_f32_e32 v101, v101
	v_exp_f32_e32 v104, v104
	v_exp_f32_e32 v105, v105
	v_exp_f32_e32 v102, v102
	v_exp_f32_e32 v103, v103
	v_pk_add_f32 v[98:99], v[98:99], 1.0 op_sel_hi:[1,0]
	v_pk_add_f32 v[100:101], v[100:101], 1.0 op_sel_hi:[1,0]
	v_pk_add_f32 v[104:105], v[104:105], 1.0 op_sel_hi:[1,0]
	v_pk_add_f32 v[102:103], v[102:103], 1.0 op_sel_hi:[1,0]
	v_rcp_f32_e32 v98, v98
	v_rcp_f32_e32 v99, v99
	v_rcp_f32_e32 v100, v100
	v_rcp_f32_e32 v101, v101
	v_rcp_f32_e32 v104, v104
	v_rcp_f32_e32 v105, v105
	v_rcp_f32_e32 v102, v102
	v_rcp_f32_e32 v103, v103
	v_cvt_f16_f32_e32 v98, v98
	v_cvt_f16_f32_sdwa v99, v99 dst_sel:WORD_1 dst_unused:UNUSED_PAD src0_sel:DWORD
	v_cvt_f16_f32_e32 v100, v100
	v_cvt_f16_f32_sdwa v101, v101 dst_sel:WORD_1 dst_unused:UNUSED_PAD src0_sel:DWORD
	v_cvt_f16_f32_e32 v104, v104
	v_cvt_f16_f32_sdwa v105, v105 dst_sel:WORD_1 dst_unused:UNUSED_PAD src0_sel:DWORD
	v_cvt_f16_f32_e32 v102, v102
	v_cvt_f16_f32_sdwa v103, v103 dst_sel:WORD_1 dst_unused:UNUSED_PAD src0_sel:DWORD
	s_and_b64 s[10:11], s[68:69], exec
	s_cselect_b32 s11, s61, s23
	s_cselect_b32 s10, s60, s22
	v_or_b32_e32 v98, v99, v98
	v_or_b32_e32 v99, v101, v100
	v_or_b32_e32 v100, v105, v104
	v_or_b32_e32 v101, v103, v102
	v_lshl_add_u64 v[112:113], s[10:11], 0, v[110:111]
	v_subrev_u32_e32 v114, s7, v172

; __device__ __forceinline__ unsigned pkh2(float lo, float hi) { _Float16 a = (_Float16)lo, b = (_Float16)hi; return (unsigned)__builtin_bit_cast(unsigned short, a) | ((unsigned)__builtin_bit_cast(unsigned short, b) << 16); }
;     template <int NA, int NM> __device__ __forceinline__ void operator()(const f32x4 (&acc)[NA][2][NM][2], const pg8::Unit& u, int ro, int wr, int wc, int fr, int fq) const {
;     ...
;                         c0.x = __builtin_amdgcn_rcpf(1.0f + __builtin_amdgcn_exp2f(v0.x * 1.4426950408889634f)); c0.y = __builtin_amdgcn_rcpf(1.0f + __builtin_amdgcn_exp2f(v0.y * 1.4426950408889634f));
;                         c0.z = __builtin_amdgcn_rcpf(1.0f + __builtin_amdgcn_exp2f(v0.z * 1.4426950408889634f)); c0.w = __builtin_amdgcn_rcpf(1.0f + __builtin_amdgcn_exp2f(v0.w * 1.4426950408889634f));
;                         c1.x = __builtin_amdgcn_rcpf(1.0f + __builtin_amdgcn_exp2f(v1.x * 1.4426950408889634f)); c1.y = __builtin_amdgcn_rcpf(1.0f + __builtin_amdgcn_exp2f(v1.y * 1.4426950408889634f));
;                         c1.z = __builtin_amdgcn_rcpf(1.0f + __builtin_amdgcn_exp2f(v1.z * 1.4426950408889634f)); c1.w = __builtin_amdgcn_rcpf(1.0f + __builtin_amdgcn_exp2f(v1.w * 1.4426950408889634f));
;                         w.x = pkh2(c0.x, c0.y); w.y = pkh2(c0.z, c0.w); w.z = pkh2(c1.x, c1.y); w.w = pkh2(c1.z, c1.w);
;                         unsigned short* dst = (type == 1 ? Ff : Fb) + (size_t)row * D + (c - type * 1024);
;                         *(u32x4*)dst = w;
.LBB0_443:
	s_andn2_b64 vcc, exec, s[70:71]
	v_lshlrev_b64 v[94:95], 11, v[106:107]
	s_cbranch_vccnz .LBB0_445
	s_mov_b32 s100, 0x3fb8aa3b
	v_pk_mul_f32 v[90:91], v[108:109], s[100:101] op_sel_hi:[1,0]
	v_pk_mul_f32 v[92:93], v[104:105], s[100:101] op_sel_hi:[1,0]
	v_pk_mul_f32 v[100:101], v[100:101], s[100:101] op_sel_hi:[1,0]
	v_pk_mul_f32 v[98:99], v[98:99], s[100:101] op_sel_hi:[1,0]
	v_exp_f32_e32 v90, v90
	v_exp_f32_e32 v91, v91
	v_exp_f32_e32 v92, v92
	v_exp_f32_e32 v93, v93
	v_exp_f32_e32 v100, v100
	v_exp_f32_e32 v101, v101
	v_exp_f32_e32 v98, v98
	v_exp_f32_e32 v99, v99
	v_pk_add_f32 v[90:91], v[90:91], 1.0 op_sel_hi:[1,0]
	v_pk_add_f32 v[92:93], v[92:93], 1.0 op_sel_hi:[1,0]
	v_pk_add_f32 v[100:101], v[100:101], 1.0 op_sel_hi:[1,0]
	v_pk_add_f32 v[98:99], v[98:99], 1.0 op_sel_hi:[1,0]
	v_rcp_f32_e32 v90, v90
	v_rcp_f32_e32 v91, v91
	v_rcp_f32_e32 v92, v92
	v_rcp_f32_e32 v93, v93
	v_rcp_f32_e32 v100, v100
	v_rcp_f32_e32 v101, v101
	v_rcp_f32_e32 v98, v98
	v_rcp_f32_e32 v99, v99
	v_cvt_f16_f32_e32 v90, v90
	v_cvt_f16_f32_sdwa v91, v91 dst_sel:WORD_1 dst_unused:UNUSED_PAD src0_sel:DWORD
	v_cvt_f16_f32_e32 v92, v92
	v_cvt_f16_f32_sdwa v93, v93 dst_sel:WORD_1 dst_unused:UNUSED_PAD src0_sel:DWORD
	v_cvt_f16_f32_e32 v100, v100
	v_cvt_f16_f32_sdwa v101, v101 dst_sel:WORD_1 dst_unused:UNUSED_PAD src0_sel:DWORD
	v_cvt_f16_f32_e32 v98, v98
	v_cvt_f16_f32_sdwa v99, v99 dst_sel:WORD_1 dst_unused:UNUSED_PAD src0_sel:DWORD
	s_and_b64 s[10:11], s[68:69], exec
	s_cselect_b32 s11, s61, s23
	s_cselect_b32 s10, s60, s22
	v_or_b32_e32 v90, v91, v90
	v_or_b32_e32 v91, v93, v92
	v_or_b32_e32 v92, v101, v100
	v_or_b32_e32 v93, v99, v98
	v_lshl_add_u64 v[110:111], s[10:11], 0, v[94:95]
	v_subrev_u32_e32 v112, s7, v156

; __device__ __forceinline__ unsigned pkh2(float lo, float hi) { _Float16 a = (_Float16)lo, b = (_Float16)hi; return (unsigned)__builtin_bit_cast(unsigned short, a) | ((unsigned)__builtin_bit_cast(unsigned short, b) << 16); }
;     template <int NA, int NM> __device__ __forceinline__ void operator()(const f32x4 (&acc)[NA][2][NM][2], const pg8::Unit& u, int ro, int wr, int wc, int fr, int fq) const {
;     ...
;                         c0.x = __builtin_amdgcn_rcpf(1.0f + __builtin_amdgcn_exp2f(v0.x * 1.4426950408889634f)); c0.y = __builtin_amdgcn_rcpf(1.0f + __builtin_amdgcn_exp2f(v0.y * 1.4426950408889634f));
;                         c0.z = __builtin_amdgcn_rcpf(1.0f + __builtin_amdgcn_exp2f(v0.z * 1.4426950408889634f)); c0.w = __builtin_amdgcn_rcpf(1.0f + __builtin_amdgcn_exp2f(v0.w * 1.4426950408889634f));
;                         c1.x = __builtin_amdgcn_rcpf(1.0f + __builtin_amdgcn_exp2f(v1.x * 1.4426950408889634f)); c1.y = __builtin_amdgcn_rcpf(1.0f + __builtin_amdgcn_exp2f(v1.y * 1.4426950408889634f));
;                         c1.z = __builtin_amdgcn_rcpf(1.0f + __builtin_amdgcn_exp2f(v1.z * 1.4426950408889634f)); c1.w = __builtin_amdgcn_rcpf(1.0f + __builtin_amdgcn_exp2f(v1.w * 1.4426950408889634f));
;                         w.x = pkh2(c0.x, c0.y); w.y = pkh2(c0.z, c0.w); w.z = pkh2(c1.x, c1.y); w.w = pkh2(c1.z, c1.w);
;                         unsigned short* dst = (type == 1 ? Ff : Fb) + (size_t)row * D + (c - type * 1024);
;                         *(u32x4*)dst = w;
.LBB0_447:
	s_andn2_b64 vcc, exec, s[70:71]
	s_cbranch_vccnz .LBB0_449
	s_mov_b32 s100, 0x3fb8aa3b
	v_pk_mul_f32 v[82:83], v[92:93], s[100:101] op_sel_hi:[1,0]
	v_pk_mul_f32 v[84:85], v[90:91], s[100:101] op_sel_hi:[1,0]
	v_pk_mul_f32 v[88:89], v[88:89], s[100:101] op_sel_hi:[1,0]
	v_pk_mul_f32 v[86:87], v[86:87], s[100:101] op_sel_hi:[1,0]
	v_exp_f32_e32 v82, v82
	v_exp_f32_e32 v83, v83
	v_exp_f32_e32 v84, v84
	v_exp_f32_e32 v85, v85
	v_exp_f32_e32 v88, v88
	v_exp_f32_e32 v89, v89
	v_exp_f32_e32 v86, v86
	v_exp_f32_e32 v87, v87
	v_pk_add_f32 v[82:83], v[82:83], 1.0 op_sel_hi:[1,0]
	v_pk_add_f32 v[84:85], v[84:85], 1.0 op_sel_hi:[1,0]
	v_pk_add_f32 v[88:89], v[88:89], 1.0 op_sel_hi:[1,0]
	v_pk_add_f32 v[86:87], v[86:87], 1.0 op_sel_hi:[1,0]
	v_rcp_f32_e32 v82, v82
	v_rcp_f32_e32 v83, v83
	v_rcp_f32_e32 v84, v84
	v_rcp_f32_e32 v85, v85
	v_rcp_f32_e32 v88, v88
	v_rcp_f32_e32 v89, v89
	v_rcp_f32_e32 v86, v86
	v_rcp_f32_e32 v87, v87
	v_cvt_f16_f32_e32 v82, v82
	v_cvt_f16_f32_sdwa v83, v83 dst_sel:WORD_1 dst_unused:UNUSED_PAD src0_sel:DWORD
	v_cvt_f16_f32_e32 v84, v84
	v_cvt_f16_f32_sdwa v85, v85 dst_sel:WORD_1 dst_unused:UNUSED_PAD src0_sel:DWORD
	v_cvt_f16_f32_e32 v88, v88
	v_cvt_f16_f32_sdwa v89, v89 dst_sel:WORD_1 dst_unused:UNUSED_PAD src0_sel:DWORD
	v_cvt_f16_f32_e32 v86, v86
	v_cvt_f16_f32_sdwa v87, v87 dst_sel:WORD_1 dst_unused:UNUSED_PAD src0_sel:DWORD
	s_and_b64 s[10:11], s[68:69], exec
	s_cselect_b32 s11, s61, s23
	s_cselect_b32 s10, s60, s22
	v_or_b32_e32 v82, v83, v82
	v_or_b32_e32 v83, v85, v84
	v_or_b32_e32 v84, v89, v88
	v_or_b32_e32 v85, v87, v86
	v_lshl_add_u64 v[96:97], s[10:11], 0, v[94:95]
	v_subrev_u32_e32 v98, s7, v172

; __device__ __forceinline__ unsigned pkh2(float lo, float hi) { _Float16 a = (_Float16)lo, b = (_Float16)hi; return (unsigned)__builtin_bit_cast(unsigned short, a) | ((unsigned)__builtin_bit_cast(unsigned short, b) << 16); }
;     template <int NA, int NM> __device__ __forceinline__ void operator()(const f32x4 (&acc)[NA][2][NM][2], const pg8::Unit& u, int ro, int wr, int wc, int fr, int fq) const {
;     ...
;                         c0.x = __builtin_amdgcn_rcpf(1.0f + __builtin_amdgcn_exp2f(v0.x * 1.4426950408889634f)); c0.y = __builtin_amdgcn_rcpf(1.0f + __builtin_amdgcn_exp2f(v0.y * 1.4426950408889634f));
;                         c0.z = __builtin_amdgcn_rcpf(1.0f + __builtin_amdgcn_exp2f(v0.z * 1.4426950408889634f)); c0.w = __builtin_amdgcn_rcpf(1.0f + __builtin_amdgcn_exp2f(v0.w * 1.4426950408889634f));
;                         c1.x = __builtin_amdgcn_rcpf(1.0f + __builtin_amdgcn_exp2f(v1.x * 1.4426950408889634f)); c1.y = __builtin_amdgcn_rcpf(1.0f + __builtin_amdgcn_exp2f(v1.y * 1.4426950408889634f));
;                         c1.z = __builtin_amdgcn_rcpf(1.0f + __builtin_amdgcn_exp2f(v1.z * 1.4426950408889634f)); c1.w = __builtin_amdgcn_rcpf(1.0f + __builtin_amdgcn_exp2f(v1.w * 1.4426950408889634f));
;                         w.x = pkh2(c0.x, c0.y); w.y = pkh2(c0.z, c0.w); w.z = pkh2(c1.x, c1.y); w.w = pkh2(c1.z, c1.w);
;                         unsigned short* dst = (type == 1 ? Ff : Fb) + (size_t)row * D + (c - type * 1024);
;                         *(u32x4*)dst = w;
.LBB0_451:
	s_andn2_b64 vcc, exec, s[70:71]
	v_lshlrev_b64 v[78:79], 11, v[90:91]
	s_cbranch_vccnz .LBB0_453
	s_mov_b32 s100, 0x3fb8aa3b
	v_pk_mul_f32 v[74:75], v[92:93], s[100:101] op_sel_hi:[1,0]
	v_pk_mul_f32 v[76:77], v[88:89], s[100:101] op_sel_hi:[1,0]
	v_pk_mul_f32 v[84:85], v[84:85], s[100:101] op_sel_hi:[1,0]
	v_pk_mul_f32 v[82:83], v[82:83], s[100:101] op_sel_hi:[1,0]
	v_exp_f32_e32 v74, v74
	v_exp_f32_e32 v75, v75
	v_exp_f32_e32 v76, v76
	v_exp_f32_e32 v77, v77
	v_exp_f32_e32 v84, v84
	v_exp_f32_e32 v85, v85
	v_exp_f32_e32 v82, v82
	v_exp_f32_e32 v83, v83
	v_pk_add_f32 v[74:75], v[74:75], 1.0 op_sel_hi:[1,0]
	v_pk_add_f32 v[76:77], v[76:77], 1.0 op_sel_hi:[1,0]
	v_pk_add_f32 v[84:85], v[84:85], 1.0 op_sel_hi:[1,0]
	v_pk_add_f32 v[82:83], v[82:83], 1.0 op_sel_hi:[1,0]
	v_rcp_f32_e32 v74, v74
	v_rcp_f32_e32 v75, v75
	v_rcp_f32_e32 v76, v76
	v_rcp_f32_e32 v77, v77
	v_rcp_f32_e32 v84, v84
	v_rcp_f32_e32 v85, v85
	v_rcp_f32_e32 v82, v82
	v_rcp_f32_e32 v83, v83
	v_cvt_f16_f32_e32 v74, v74
	v_cvt_f16_f32_sdwa v75, v75 dst_sel:WORD_1 dst_unused:UNUSED_PAD src0_sel:DWORD
	v_cvt_f16_f32_e32 v76, v76
	v_cvt_f16_f32_sdwa v77, v77 dst_sel:WORD_1 dst_unused:UNUSED_PAD src0_sel:DWORD
	v_cvt_f16_f32_e32 v84, v84
	v_cvt_f16_f32_sdwa v85, v85 dst_sel:WORD_1 dst_unused:UNUSED_PAD src0_sel:DWORD
	v_cvt_f16_f32_e32 v82, v82
	v_cvt_f16_f32_sdwa v83, v83 dst_sel:WORD_1 dst_unused:UNUSED_PAD src0_sel:DWORD
	s_and_b64 s[10:11], s[68:69], exec
	s_cselect_b32 s11, s61, s23
	s_cselect_b32 s10, s60, s22
	v_or_b32_e32 v74, v75, v74
	v_or_b32_e32 v75, v77, v76
	v_or_b32_e32 v76, v85, v84
	v_or_b32_e32 v77, v83, v82
	v_lshl_add_u64 v[94:95], s[10:11], 0, v[78:79]
	v_subrev_u32_e32 v96, s7, v156

; __device__ __forceinline__ unsigned pkh2(float lo, float hi) { _Float16 a = (_Float16)lo, b = (_Float16)hi; return (unsigned)__builtin_bit_cast(unsigned short, a) | ((unsigned)__builtin_bit_cast(unsigned short, b) << 16); }
;     template <int NA, int NM> __device__ __forceinline__ void operator()(const f32x4 (&acc)[NA][2][NM][2], const pg8::Unit& u, int ro, int wr, int wc, int fr, int fq) const {
;     ...
;                         c0.x = __builtin_amdgcn_rcpf(1.0f + __builtin_amdgcn_exp2f(v0.x * 1.4426950408889634f)); c0.y = __builtin_amdgcn_rcpf(1.0f + __builtin_amdgcn_exp2f(v0.y * 1.4426950408889634f));
;                         c0.z = __builtin_amdgcn_rcpf(1.0f + __builtin_amdgcn_exp2f(v0.z * 1.4426950408889634f)); c0.w = __builtin_amdgcn_rcpf(1.0f + __builtin_amdgcn_exp2f(v0.w * 1.4426950408889634f));
;                         c1.x = __builtin_amdgcn_rcpf(1.0f + __builtin_amdgcn_exp2f(v1.x * 1.4426950408889634f)); c1.y = __builtin_amdgcn_rcpf(1.0f + __builtin_amdgcn_exp2f(v1.y * 1.4426950408889634f));
;                         c1.z = __builtin_amdgcn_rcpf(1.0f + __builtin_amdgcn_exp2f(v1.z * 1.4426950408889634f)); c1.w = __builtin_amdgcn_rcpf(1.0f + __builtin_amdgcn_exp2f(v1.w * 1.4426950408889634f));
;                         w.x = pkh2(c0.x, c0.y); w.y = pkh2(c0.z, c0.w); w.z = pkh2(c1.x, c1.y); w.w = pkh2(c1.z, c1.w);
;                         unsigned short* dst = (type == 1 ? Ff : Fb) + (size_t)row * D + (c - type * 1024);
;                         *(u32x4*)dst = w;
.LBB0_455:
	s_andn2_b64 vcc, exec, s[70:71]
	s_cbranch_vccnz .LBB0_457
	s_mov_b32 s100, 0x3fb8aa3b
	v_pk_mul_f32 v[58:59], v[76:77], s[100:101] op_sel_hi:[1,0]
	v_pk_mul_f32 v[60:61], v[74:75], s[100:101] op_sel_hi:[1,0]
	v_pk_mul_f32 v[64:65], v[64:65], s[100:101] op_sel_hi:[1,0]
	v_pk_mul_f32 v[62:63], v[62:63], s[100:101] op_sel_hi:[1,0]
	v_exp_f32_e32 v58, v58
	v_exp_f32_e32 v59, v59
	v_exp_f32_e32 v60, v60
	v_exp_f32_e32 v61, v61
	v_exp_f32_e32 v64, v64
	v_exp_f32_e32 v65, v65
	v_exp_f32_e32 v62, v62
	v_exp_f32_e32 v63, v63
	v_pk_add_f32 v[58:59], v[58:59], 1.0 op_sel_hi:[1,0]
	v_pk_add_f32 v[60:61], v[60:61], 1.0 op_sel_hi:[1,0]
	v_pk_add_f32 v[64:65], v[64:65], 1.0 op_sel_hi:[1,0]
	v_pk_add_f32 v[62:63], v[62:63], 1.0 op_sel_hi:[1,0]
	v_rcp_f32_e32 v58, v58
	v_rcp_f32_e32 v59, v59
	v_rcp_f32_e32 v60, v60
	v_rcp_f32_e32 v61, v61
	v_rcp_f32_e32 v64, v64
	v_rcp_f32_e32 v65, v65
	v_rcp_f32_e32 v62, v62
	v_rcp_f32_e32 v63, v63
	v_cvt_f16_f32_e32 v58, v58
	v_cvt_f16_f32_sdwa v59, v59 dst_sel:WORD_1 dst_unused:UNUSED_PAD src0_sel:DWORD
	v_cvt_f16_f32_e32 v60, v60
	v_cvt_f16_f32_sdwa v61, v61 dst_sel:WORD_1 dst_unused:UNUSED_PAD src0_sel:DWORD
	v_cvt_f16_f32_e32 v64, v64
	v_cvt_f16_f32_sdwa v65, v65 dst_sel:WORD_1 dst_unused:UNUSED_PAD src0_sel:DWORD
	v_cvt_f16_f32_e32 v62, v62
	v_cvt_f16_f32_sdwa v63, v63 dst_sel:WORD_1 dst_unused:UNUSED_PAD src0_sel:DWORD
	s_and_b64 s[10:11], s[68:69], exec
	s_cselect_b32 s11, s61, s23
	s_cselect_b32 s10, s60, s22
	v_or_b32_e32 v58, v59, v58
	v_or_b32_e32 v59, v61, v60
	v_or_b32_e32 v60, v65, v64
	v_or_b32_e32 v61, v63, v62
	v_lshl_add_u64 v[80:81], s[10:11], 0, v[78:79]
	v_subrev_u32_e32 v82, s7, v172

; __device__ __forceinline__ unsigned pkh2(float lo, float hi) { _Float16 a = (_Float16)lo, b = (_Float16)hi; return (unsigned)__builtin_bit_cast(unsigned short, a) | ((unsigned)__builtin_bit_cast(unsigned short, b) << 16); }
;     template <int NA, int NM> __device__ __forceinline__ void operator()(const f32x4 (&acc)[NA][2][NM][2], const pg8::Unit& u, int ro, int wr, int wc, int fr, int fq) const {
;     ...
;                         c0.x = __builtin_amdgcn_rcpf(1.0f + __builtin_amdgcn_exp2f(v0.x * 1.4426950408889634f)); c0.y = __builtin_amdgcn_rcpf(1.0f + __builtin_amdgcn_exp2f(v0.y * 1.4426950408889634f));
;                         c0.z = __builtin_amdgcn_rcpf(1.0f + __builtin_amdgcn_exp2f(v0.z * 1.4426950408889634f)); c0.w = __builtin_amdgcn_rcpf(1.0f + __builtin_amdgcn_exp2f(v0.w * 1.4426950408889634f));
;                         c1.x = __builtin_amdgcn_rcpf(1.0f + __builtin_amdgcn_exp2f(v1.x * 1.4426950408889634f)); c1.y = __builtin_amdgcn_rcpf(1.0f + __builtin_amdgcn_exp2f(v1.y * 1.4426950408889634f));
;                         c1.z = __builtin_amdgcn_rcpf(1.0f + __builtin_amdgcn_exp2f(v1.z * 1.4426950408889634f)); c1.w = __builtin_amdgcn_rcpf(1.0f + __builtin_amdgcn_exp2f(v1.w * 1.4426950408889634f));
;                         w.x = pkh2(c0.x, c0.y); w.y = pkh2(c0.z, c0.w); w.z = pkh2(c1.x, c1.y); w.w = pkh2(c1.z, c1.w);
;                         unsigned short* dst = (type == 1 ? Ff : Fb) + (size_t)row * D + (c - type * 1024);
;                         *(u32x4*)dst = w;
.LBB0_459:
	s_andn2_b64 vcc, exec, s[70:71]
	v_lshlrev_b64 v[46:47], 11, v[74:75]
	s_cbranch_vccnz .LBB0_461
	s_mov_b32 s100, 0x3fb8aa3b
	v_pk_mul_f32 v[42:43], v[76:77], s[100:101] op_sel_hi:[1,0]
	v_pk_mul_f32 v[44:45], v[64:65], s[100:101] op_sel_hi:[1,0]
	v_pk_mul_f32 v[60:61], v[60:61], s[100:101] op_sel_hi:[1,0]
	v_pk_mul_f32 v[58:59], v[58:59], s[100:101] op_sel_hi:[1,0]
	v_exp_f32_e32 v42, v42
	v_exp_f32_e32 v43, v43
	v_exp_f32_e32 v44, v44
	v_exp_f32_e32 v45, v45
	v_exp_f32_e32 v60, v60
	v_exp_f32_e32 v61, v61
	v_exp_f32_e32 v58, v58
	v_exp_f32_e32 v59, v59
	v_pk_add_f32 v[42:43], v[42:43], 1.0 op_sel_hi:[1,0]
	v_pk_add_f32 v[44:45], v[44:45], 1.0 op_sel_hi:[1,0]
	v_pk_add_f32 v[60:61], v[60:61], 1.0 op_sel_hi:[1,0]
	v_pk_add_f32 v[58:59], v[58:59], 1.0 op_sel_hi:[1,0]
	v_rcp_f32_e32 v42, v42
	v_rcp_f32_e32 v43, v43
	v_rcp_f32_e32 v44, v44
	v_rcp_f32_e32 v45, v45
	v_rcp_f32_e32 v60, v60
	v_rcp_f32_e32 v61, v61
	v_rcp_f32_e32 v58, v58
	v_rcp_f32_e32 v59, v59
	v_cvt_f16_f32_e32 v42, v42
	v_cvt_f16_f32_sdwa v43, v43 dst_sel:WORD_1 dst_unused:UNUSED_PAD src0_sel:DWORD
	v_cvt_f16_f32_e32 v44, v44
	v_cvt_f16_f32_sdwa v45, v45 dst_sel:WORD_1 dst_unused:UNUSED_PAD src0_sel:DWORD
	v_cvt_f16_f32_e32 v60, v60
	v_cvt_f16_f32_sdwa v61, v61 dst_sel:WORD_1 dst_unused:UNUSED_PAD src0_sel:DWORD
	v_cvt_f16_f32_e32 v58, v58
	v_cvt_f16_f32_sdwa v59, v59 dst_sel:WORD_1 dst_unused:UNUSED_PAD src0_sel:DWORD
	s_and_b64 s[10:11], s[68:69], exec
	s_cselect_b32 s11, s61, s23
	s_cselect_b32 s10, s60, s22
	v_or_b32_e32 v42, v43, v42
	v_or_b32_e32 v43, v45, v44
	v_or_b32_e32 v44, v61, v60
	v_or_b32_e32 v45, v59, v58
	v_lshl_add_u64 v[78:79], s[10:11], 0, v[46:47]
	v_subrev_u32_e32 v80, s7, v156

; __device__ __forceinline__ unsigned pkh2(float lo, float hi) { _Float16 a = (_Float16)lo, b = (_Float16)hi; return (unsigned)__builtin_bit_cast(unsigned short, a) | ((unsigned)__builtin_bit_cast(unsigned short, b) << 16); }
;     template <int NA, int NM> __device__ __forceinline__ void operator()(const f32x4 (&acc)[NA][2][NM][2], const pg8::Unit& u, int ro, int wr, int wc, int fr, int fq) const {
;     ...
;                         c0.x = __builtin_amdgcn_rcpf(1.0f + __builtin_amdgcn_exp2f(v0.x * 1.4426950408889634f)); c0.y = __builtin_amdgcn_rcpf(1.0f + __builtin_amdgcn_exp2f(v0.y * 1.4426950408889634f));
;                         c0.z = __builtin_amdgcn_rcpf(1.0f + __builtin_amdgcn_exp2f(v0.z * 1.4426950408889634f)); c0.w = __builtin_amdgcn_rcpf(1.0f + __builtin_amdgcn_exp2f(v0.w * 1.4426950408889634f));
;                         c1.x = __builtin_amdgcn_rcpf(1.0f + __builtin_amdgcn_exp2f(v1.x * 1.4426950408889634f)); c1.y = __builtin_amdgcn_rcpf(1.0f + __builtin_amdgcn_exp2f(v1.y * 1.4426950408889634f));
;                         c1.z = __builtin_amdgcn_rcpf(1.0f + __builtin_amdgcn_exp2f(v1.z * 1.4426950408889634f)); c1.w = __builtin_amdgcn_rcpf(1.0f + __builtin_amdgcn_exp2f(v1.w * 1.4426950408889634f));
;                         w.x = pkh2(c0.x, c0.y); w.y = pkh2(c0.z, c0.w); w.z = pkh2(c1.x, c1.y); w.w = pkh2(c1.z, c1.w);
;                         unsigned short* dst = (type == 1 ? Ff : Fb) + (size_t)row * D + (c - type * 1024);
;                         *(u32x4*)dst = w;
.LBB0_463:
	s_andn2_b64 vcc, exec, s[70:71]
	s_cbranch_vccnz .LBB0_465
	s_mov_b32 s100, 0x3fb8aa3b
	v_pk_mul_f32 v[34:35], v[44:45], s[100:101] op_sel_hi:[1,0]
	v_pk_mul_f32 v[36:37], v[42:43], s[100:101] op_sel_hi:[1,0]
	v_pk_mul_f32 v[40:41], v[40:41], s[100:101] op_sel_hi:[1,0]
	v_pk_mul_f32 v[38:39], v[38:39], s[100:101] op_sel_hi:[1,0]
	v_exp_f32_e32 v34, v34
	v_exp_f32_e32 v35, v35
	v_exp_f32_e32 v36, v36
	v_exp_f32_e32 v37, v37
	v_exp_f32_e32 v40, v40
	v_exp_f32_e32 v41, v41
	v_exp_f32_e32 v38, v38
	v_exp_f32_e32 v39, v39
	v_pk_add_f32 v[34:35], v[34:35], 1.0 op_sel_hi:[1,0]
	v_pk_add_f32 v[36:37], v[36:37], 1.0 op_sel_hi:[1,0]
	v_pk_add_f32 v[40:41], v[40:41], 1.0 op_sel_hi:[1,0]
	v_pk_add_f32 v[38:39], v[38:39], 1.0 op_sel_hi:[1,0]
	v_rcp_f32_e32 v34, v34
	v_rcp_f32_e32 v35, v35
	v_rcp_f32_e32 v36, v36
	v_rcp_f32_e32 v37, v37
	v_rcp_f32_e32 v40, v40
	v_rcp_f32_e32 v41, v41
	v_rcp_f32_e32 v38, v38
	v_rcp_f32_e32 v39, v39
	v_cvt_f16_f32_e32 v34, v34
	v_cvt_f16_f32_sdwa v35, v35 dst_sel:WORD_1 dst_unused:UNUSED_PAD src0_sel:DWORD
	v_cvt_f16_f32_e32 v36, v36
	v_cvt_f16_f32_sdwa v37, v37 dst_sel:WORD_1 dst_unused:UNUSED_PAD src0_sel:DWORD
	v_cvt_f16_f32_e32 v40, v40
	v_cvt_f16_f32_sdwa v41, v41 dst_sel:WORD_1 dst_unused:UNUSED_PAD src0_sel:DWORD
	v_cvt_f16_f32_e32 v38, v38
	v_cvt_f16_f32_sdwa v39, v39 dst_sel:WORD_1 dst_unused:UNUSED_PAD src0_sel:DWORD
	s_and_b64 s[10:11], s[68:69], exec
	s_cselect_b32 s11, s61, s23
	s_cselect_b32 s10, s60, s22
	v_or_b32_e32 v34, v35, v34
	v_or_b32_e32 v35, v37, v36
	v_or_b32_e32 v36, v41, v40
	v_or_b32_e32 v37, v39, v38
	v_lshl_add_u64 v[48:49], s[10:11], 0, v[46:47]
	v_subrev_u32_e32 v58, s7, v172

; __device__ __forceinline__ unsigned pkh2(float lo, float hi) { _Float16 a = (_Float16)lo, b = (_Float16)hi; return (unsigned)__builtin_bit_cast(unsigned short, a) | ((unsigned)__builtin_bit_cast(unsigned short, b) << 16); }
;     template <int NA, int NM> __device__ __forceinline__ void operator()(const f32x4 (&acc)[NA][2][NM][2], const pg8::Unit& u, int ro, int wr, int wc, int fr, int fq) const {
;     ...
;                         c0.x = __builtin_amdgcn_rcpf(1.0f + __builtin_amdgcn_exp2f(v0.x * 1.4426950408889634f)); c0.y = __builtin_amdgcn_rcpf(1.0f + __builtin_amdgcn_exp2f(v0.y * 1.4426950408889634f));
;                         c0.z = __builtin_amdgcn_rcpf(1.0f + __builtin_amdgcn_exp2f(v0.z * 1.4426950408889634f)); c0.w = __builtin_amdgcn_rcpf(1.0f + __builtin_amdgcn_exp2f(v0.w * 1.4426950408889634f));
;                         c1.x = __builtin_amdgcn_rcpf(1.0f + __builtin_amdgcn_exp2f(v1.x * 1.4426950408889634f)); c1.y = __builtin_amdgcn_rcpf(1.0f + __builtin_amdgcn_exp2f(v1.y * 1.4426950408889634f));
;                         c1.z = __builtin_amdgcn_rcpf(1.0f + __builtin_amdgcn_exp2f(v1.z * 1.4426950408889634f)); c1.w = __builtin_amdgcn_rcpf(1.0f + __builtin_amdgcn_exp2f(v1.w * 1.4426950408889634f));
;                         w.x = pkh2(c0.x, c0.y); w.y = pkh2(c0.z, c0.w); w.z = pkh2(c1.x, c1.y); w.w = pkh2(c1.z, c1.w);
;                         unsigned short* dst = (type == 1 ? Ff : Fb) + (size_t)row * D + (c - type * 1024);
;                         *(u32x4*)dst = w;
.LBB0_467:
	s_andn2_b64 vcc, exec, s[70:71]
	v_lshlrev_b64 v[30:31], 11, v[42:43]
	s_cbranch_vccnz .LBB0_469
	s_mov_b32 s100, 0x3fb8aa3b
	v_pk_mul_f32 v[26:27], v[44:45], s[100:101] op_sel_hi:[1,0]
	v_pk_mul_f32 v[28:29], v[40:41], s[100:101] op_sel_hi:[1,0]
	v_pk_mul_f32 v[36:37], v[36:37], s[100:101] op_sel_hi:[1,0]
	v_pk_mul_f32 v[34:35], v[34:35], s[100:101] op_sel_hi:[1,0]
	v_exp_f32_e32 v26, v26
	v_exp_f32_e32 v27, v27
	v_exp_f32_e32 v28, v28
	v_exp_f32_e32 v29, v29
	v_exp_f32_e32 v36, v36
	v_exp_f32_e32 v37, v37
	v_exp_f32_e32 v34, v34
	v_exp_f32_e32 v35, v35
	v_pk_add_f32 v[26:27], v[26:27], 1.0 op_sel_hi:[1,0]
	v_pk_add_f32 v[28:29], v[28:29], 1.0 op_sel_hi:[1,0]
	v_pk_add_f32 v[36:37], v[36:37], 1.0 op_sel_hi:[1,0]
	v_pk_add_f32 v[34:35], v[34:35], 1.0 op_sel_hi:[1,0]
	v_rcp_f32_e32 v26, v26
	v_rcp_f32_e32 v27, v27
	v_rcp_f32_e32 v28, v28
	v_rcp_f32_e32 v29, v29
	v_rcp_f32_e32 v36, v36
	v_rcp_f32_e32 v37, v37
	v_rcp_f32_e32 v34, v34
	v_rcp_f32_e32 v35, v35
	v_cvt_f16_f32_e32 v26, v26
	v_cvt_f16_f32_sdwa v27, v27 dst_sel:WORD_1 dst_unused:UNUSED_PAD src0_sel:DWORD
	v_cvt_f16_f32_e32 v28, v28
	v_cvt_f16_f32_sdwa v29, v29 dst_sel:WORD_1 dst_unused:UNUSED_PAD src0_sel:DWORD
	v_cvt_f16_f32_e32 v36, v36
	v_cvt_f16_f32_sdwa v37, v37 dst_sel:WORD_1 dst_unused:UNUSED_PAD src0_sel:DWORD
	v_cvt_f16_f32_e32 v34, v34
	v_cvt_f16_f32_sdwa v35, v35 dst_sel:WORD_1 dst_unused:UNUSED_PAD src0_sel:DWORD
	s_and_b64 s[10:11], s[68:69], exec
	s_cselect_b32 s11, s61, s23
	s_cselect_b32 s10, s60, s22
	v_or_b32_e32 v26, v27, v26
	v_or_b32_e32 v27, v29, v28
	v_or_b32_e32 v28, v37, v36
	v_or_b32_e32 v29, v35, v34
	v_lshl_add_u64 v[46:47], s[10:11], 0, v[30:31]
	v_subrev_u32_e32 v48, s7, v156

; __device__ __forceinline__ unsigned pkh2(float lo, float hi) { _Float16 a = (_Float16)lo, b = (_Float16)hi; return (unsigned)__builtin_bit_cast(unsigned short, a) | ((unsigned)__builtin_bit_cast(unsigned short, b) << 16); }
;     template <int NA, int NM> __device__ __forceinline__ void operator()(const f32x4 (&acc)[NA][2][NM][2], const pg8::Unit& u, int ro, int wr, int wc, int fr, int fq) const {
;     ...
;                         c0.x = __builtin_amdgcn_rcpf(1.0f + __builtin_amdgcn_exp2f(v0.x * 1.4426950408889634f)); c0.y = __builtin_amdgcn_rcpf(1.0f + __builtin_amdgcn_exp2f(v0.y * 1.4426950408889634f));
;                         c0.z = __builtin_amdgcn_rcpf(1.0f + __builtin_amdgcn_exp2f(v0.z * 1.4426950408889634f)); c0.w = __builtin_amdgcn_rcpf(1.0f + __builtin_amdgcn_exp2f(v0.w * 1.4426950408889634f));
;                         c1.x = __builtin_amdgcn_rcpf(1.0f + __builtin_amdgcn_exp2f(v1.x * 1.4426950408889634f)); c1.y = __builtin_amdgcn_rcpf(1.0f + __builtin_amdgcn_exp2f(v1.y * 1.4426950408889634f));
;                         c1.z = __builtin_amdgcn_rcpf(1.0f + __builtin_amdgcn_exp2f(v1.z * 1.4426950408889634f)); c1.w = __builtin_amdgcn_rcpf(1.0f + __builtin_amdgcn_exp2f(v1.w * 1.4426950408889634f));
;                         w.x = pkh2(c0.x, c0.y); w.y = pkh2(c0.z, c0.w); w.z = pkh2(c1.x, c1.y); w.w = pkh2(c1.z, c1.w);
;                         unsigned short* dst = (type == 1 ? Ff : Fb) + (size_t)row * D + (c - type * 1024);
;                         *(u32x4*)dst = w;
.LBB0_471:
	s_andn2_b64 vcc, exec, s[70:71]
	s_cbranch_vccnz .LBB0_473
	s_mov_b32 s100, 0x3fb8aa3b
	v_pk_mul_f32 v[18:19], v[28:29], s[100:101] op_sel_hi:[1,0]
	v_pk_mul_f32 v[20:21], v[26:27], s[100:101] op_sel_hi:[1,0]
	v_pk_mul_f32 v[24:25], v[24:25], s[100:101] op_sel_hi:[1,0]
	v_pk_mul_f32 v[22:23], v[22:23], s[100:101] op_sel_hi:[1,0]
	v_exp_f32_e32 v18, v18
	v_exp_f32_e32 v19, v19
	v_exp_f32_e32 v20, v20
	v_exp_f32_e32 v21, v21
	v_exp_f32_e32 v24, v24
	v_exp_f32_e32 v25, v25
	v_exp_f32_e32 v22, v22
	v_exp_f32_e32 v23, v23
	v_pk_add_f32 v[18:19], v[18:19], 1.0 op_sel_hi:[1,0]
	v_pk_add_f32 v[20:21], v[20:21], 1.0 op_sel_hi:[1,0]
	v_pk_add_f32 v[24:25], v[24:25], 1.0 op_sel_hi:[1,0]
	v_pk_add_f32 v[22:23], v[22:23], 1.0 op_sel_hi:[1,0]
	v_rcp_f32_e32 v18, v18
	v_rcp_f32_e32 v19, v19
	v_rcp_f32_e32 v20, v20
	v_rcp_f32_e32 v21, v21
	v_rcp_f32_e32 v24, v24
	v_rcp_f32_e32 v25, v25
	v_rcp_f32_e32 v22, v22
	v_rcp_f32_e32 v23, v23
	v_cvt_f16_f32_e32 v18, v18
	v_cvt_f16_f32_sdwa v19, v19 dst_sel:WORD_1 dst_unused:UNUSED_PAD src0_sel:DWORD
	v_cvt_f16_f32_e32 v20, v20
	v_cvt_f16_f32_sdwa v21, v21 dst_sel:WORD_1 dst_unused:UNUSED_PAD src0_sel:DWORD
	v_cvt_f16_f32_e32 v24, v24
	v_cvt_f16_f32_sdwa v25, v25 dst_sel:WORD_1 dst_unused:UNUSED_PAD src0_sel:DWORD
	v_cvt_f16_f32_e32 v22, v22
	v_cvt_f16_f32_sdwa v23, v23 dst_sel:WORD_1 dst_unused:UNUSED_PAD src0_sel:DWORD
	s_and_b64 s[10:11], s[68:69], exec
	s_cselect_b32 s11, s61, s23
	s_cselect_b32 s10, s60, s22
	v_or_b32_e32 v18, v19, v18
	v_or_b32_e32 v19, v21, v20
	v_or_b32_e32 v20, v25, v24
	v_or_b32_e32 v21, v23, v22
	v_lshl_add_u64 v[32:33], s[10:11], 0, v[30:31]
	v_subrev_u32_e32 v34, s7, v172

; __device__ __forceinline__ unsigned pkh2(float lo, float hi) { _Float16 a = (_Float16)lo, b = (_Float16)hi; return (unsigned)__builtin_bit_cast(unsigned short, a) | ((unsigned)__builtin_bit_cast(unsigned short, b) << 16); }
;     template <int NA, int NM> __device__ __forceinline__ void operator()(const f32x4 (&acc)[NA][2][NM][2], const pg8::Unit& u, int ro, int wr, int wc, int fr, int fq) const {
;     ...
;                         c0.x = __builtin_amdgcn_rcpf(1.0f + __builtin_amdgcn_exp2f(v0.x * 1.4426950408889634f)); c0.y = __builtin_amdgcn_rcpf(1.0f + __builtin_amdgcn_exp2f(v0.y * 1.4426950408889634f));
;                         c0.z = __builtin_amdgcn_rcpf(1.0f + __builtin_amdgcn_exp2f(v0.z * 1.4426950408889634f)); c0.w = __builtin_amdgcn_rcpf(1.0f + __builtin_amdgcn_exp2f(v0.w * 1.4426950408889634f));
;                         c1.x = __builtin_amdgcn_rcpf(1.0f + __builtin_amdgcn_exp2f(v1.x * 1.4426950408889634f)); c1.y = __builtin_amdgcn_rcpf(1.0f + __builtin_amdgcn_exp2f(v1.y * 1.4426950408889634f));
;                         c1.z = __builtin_amdgcn_rcpf(1.0f + __builtin_amdgcn_exp2f(v1.z * 1.4426950408889634f)); c1.w = __builtin_amdgcn_rcpf(1.0f + __builtin_amdgcn_exp2f(v1.w * 1.4426950408889634f));
;                         w.x = pkh2(c0.x, c0.y); w.y = pkh2(c0.z, c0.w); w.z = pkh2(c1.x, c1.y); w.w = pkh2(c1.z, c1.w);
;                         unsigned short* dst = (type == 1 ? Ff : Fb) + (size_t)row * D + (c - type * 1024);
;                         *(u32x4*)dst = w;
.LBB0_475:
	s_andn2_b64 vcc, exec, s[64:65]
	v_lshlrev_b64 v[14:15], 11, v[26:27]
	s_cbranch_vccnz .LBB0_477
	s_mov_b32 s100, 0x3fb8aa3b
	v_pk_mul_f32 v[10:11], v[28:29], s[100:101] op_sel_hi:[1,0]
	v_pk_mul_f32 v[12:13], v[24:25], s[100:101] op_sel_hi:[1,0]
	v_pk_mul_f32 v[20:21], v[20:21], s[100:101] op_sel_hi:[1,0]
	v_pk_mul_f32 v[18:19], v[18:19], s[100:101] op_sel_hi:[1,0]
	v_exp_f32_e32 v10, v10
	v_exp_f32_e32 v11, v11
	v_exp_f32_e32 v12, v12
	v_exp_f32_e32 v13, v13
	v_exp_f32_e32 v20, v20
	v_exp_f32_e32 v21, v21
	v_exp_f32_e32 v18, v18
	v_exp_f32_e32 v19, v19
	v_pk_add_f32 v[10:11], v[10:11], 1.0 op_sel_hi:[1,0]
	v_pk_add_f32 v[12:13], v[12:13], 1.0 op_sel_hi:[1,0]
	v_pk_add_f32 v[20:21], v[20:21], 1.0 op_sel_hi:[1,0]
	v_pk_add_f32 v[18:19], v[18:19], 1.0 op_sel_hi:[1,0]
	v_rcp_f32_e32 v10, v10
	v_rcp_f32_e32 v11, v11
	v_rcp_f32_e32 v12, v12
	v_rcp_f32_e32 v13, v13
	v_rcp_f32_e32 v20, v20
	v_rcp_f32_e32 v21, v21
	v_rcp_f32_e32 v18, v18
	v_rcp_f32_e32 v19, v19
	v_cvt_f16_f32_e32 v10, v10
	v_cvt_f16_f32_sdwa v11, v11 dst_sel:WORD_1 dst_unused:UNUSED_PAD src0_sel:DWORD
	v_cvt_f16_f32_e32 v12, v12
	v_cvt_f16_f32_sdwa v13, v13 dst_sel:WORD_1 dst_unused:UNUSED_PAD src0_sel:DWORD
	v_cvt_f16_f32_e32 v20, v20
	v_cvt_f16_f32_sdwa v21, v21 dst_sel:WORD_1 dst_unused:UNUSED_PAD src0_sel:DWORD
	v_cvt_f16_f32_e32 v18, v18
	v_cvt_f16_f32_sdwa v19, v19 dst_sel:WORD_1 dst_unused:UNUSED_PAD src0_sel:DWORD
	s_and_b64 s[10:11], s[68:69], exec
	s_cselect_b32 s11, s61, s23
	s_cselect_b32 s10, s60, s22
	v_or_b32_e32 v10, v11, v10
	v_or_b32_e32 v11, v13, v12
	v_or_b32_e32 v12, v21, v20
	v_or_b32_e32 v13, v19, v18
	v_lshl_add_u64 v[30:31], s[10:11], 0, v[14:15]
	v_mov_b32_e32 v142, v143

; __device__ __forceinline__ unsigned pkh2(float lo, float hi) { _Float16 a = (_Float16)lo, b = (_Float16)hi; return (unsigned)__builtin_bit_cast(unsigned short, a) | ((unsigned)__builtin_bit_cast(unsigned short, b) << 16); }
;     template <int NA, int NM> __device__ __forceinline__ void operator()(const f32x4 (&acc)[NA][2][NM][2], const pg8::Unit& u, int ro, int wr, int wc, int fr, int fq) const {
;     ...
;                         c0.x = __builtin_amdgcn_rcpf(1.0f + __builtin_amdgcn_exp2f(v0.x * 1.4426950408889634f)); c0.y = __builtin_amdgcn_rcpf(1.0f + __builtin_amdgcn_exp2f(v0.y * 1.4426950408889634f));
;                         c0.z = __builtin_amdgcn_rcpf(1.0f + __builtin_amdgcn_exp2f(v0.z * 1.4426950408889634f)); c0.w = __builtin_amdgcn_rcpf(1.0f + __builtin_amdgcn_exp2f(v0.w * 1.4426950408889634f));
;                         c1.x = __builtin_amdgcn_rcpf(1.0f + __builtin_amdgcn_exp2f(v1.x * 1.4426950408889634f)); c1.y = __builtin_amdgcn_rcpf(1.0f + __builtin_amdgcn_exp2f(v1.y * 1.4426950408889634f));
;                         c1.z = __builtin_amdgcn_rcpf(1.0f + __builtin_amdgcn_exp2f(v1.z * 1.4426950408889634f)); c1.w = __builtin_amdgcn_rcpf(1.0f + __builtin_amdgcn_exp2f(v1.w * 1.4426950408889634f));
;                         w.x = pkh2(c0.x, c0.y); w.y = pkh2(c0.z, c0.w); w.z = pkh2(c1.x, c1.y); w.w = pkh2(c1.z, c1.w);
;                         unsigned short* dst = (type == 1 ? Ff : Fb) + (size_t)row * D + (c - type * 1024);
;                         *(u32x4*)dst = w;
.LBB0_479:
	s_andn2_b64 vcc, exec, s[64:65]
	s_cbranch_vccnz .LBB0_481
	s_mov_b32 s100, 0x3fb8aa3b
	v_pk_mul_f32 v[2:3], v[12:13], s[100:101] op_sel_hi:[1,0]
	v_pk_mul_f32 v[4:5], v[10:11], s[100:101] op_sel_hi:[1,0]
	v_pk_mul_f32 v[8:9], v[8:9], s[100:101] op_sel_hi:[1,0]
	v_pk_mul_f32 v[6:7], v[6:7], s[100:101] op_sel_hi:[1,0]
	v_exp_f32_e32 v2, v2
	v_exp_f32_e32 v3, v3
	v_exp_f32_e32 v4, v4
	v_exp_f32_e32 v5, v5
	v_exp_f32_e32 v8, v8
	v_exp_f32_e32 v9, v9
	v_exp_f32_e32 v6, v6
	v_exp_f32_e32 v7, v7
	v_pk_add_f32 v[2:3], v[2:3], 1.0 op_sel_hi:[1,0]
	v_pk_add_f32 v[4:5], v[4:5], 1.0 op_sel_hi:[1,0]
	v_pk_add_f32 v[8:9], v[8:9], 1.0 op_sel_hi:[1,0]
	v_pk_add_f32 v[6:7], v[6:7], 1.0 op_sel_hi:[1,0]
	v_rcp_f32_e32 v2, v2
	v_rcp_f32_e32 v3, v3
	v_rcp_f32_e32 v4, v4
	v_rcp_f32_e32 v5, v5
	v_rcp_f32_e32 v8, v8
	v_rcp_f32_e32 v9, v9
	v_rcp_f32_e32 v6, v6
	v_rcp_f32_e32 v7, v7
	v_cvt_f16_f32_e32 v2, v2
	v_cvt_f16_f32_sdwa v3, v3 dst_sel:WORD_1 dst_unused:UNUSED_PAD src0_sel:DWORD
	v_cvt_f16_f32_e32 v4, v4
	v_cvt_f16_f32_sdwa v5, v5 dst_sel:WORD_1 dst_unused:UNUSED_PAD src0_sel:DWORD
	v_cvt_f16_f32_e32 v8, v8
	v_cvt_f16_f32_sdwa v9, v9 dst_sel:WORD_1 dst_unused:UNUSED_PAD src0_sel:DWORD
	v_cvt_f16_f32_e32 v6, v6
	v_cvt_f16_f32_sdwa v7, v7 dst_sel:WORD_1 dst_unused:UNUSED_PAD src0_sel:DWORD
	s_and_b64 s[10:11], s[68:69], exec
	s_cselect_b32 s11, s61, s23
	s_cselect_b32 s10, s60, s22
	v_or_b32_e32 v2, v3, v2
	v_or_b32_e32 v3, v5, v4
	v_or_b32_e32 v4, v9, v8
	v_or_b32_e32 v5, v7, v6
	v_lshl_add_u64 v[16:17], s[10:11], 0, v[14:15]
	v_mov_b32_e32 v134, v135

; __device__ __forceinline__ unsigned pkh2(float lo, float hi) { _Float16 a = (_Float16)lo, b = (_Float16)hi; return (unsigned)__builtin_bit_cast(unsigned short, a) | ((unsigned)__builtin_bit_cast(unsigned short, b) << 16); }
;     template <int NA, int NM> __device__ __forceinline__ void operator()(const f32x4 (&acc)[NA][2][NM][2], const pg8::Unit& u, int ro, int wr, int wc, int fr, int fq) const {
;     ...
;                         c0.x = __builtin_amdgcn_rcpf(1.0f + __builtin_amdgcn_exp2f(v0.x * 1.4426950408889634f)); c0.y = __builtin_amdgcn_rcpf(1.0f + __builtin_amdgcn_exp2f(v0.y * 1.4426950408889634f));
;                         c0.z = __builtin_amdgcn_rcpf(1.0f + __builtin_amdgcn_exp2f(v0.z * 1.4426950408889634f)); c0.w = __builtin_amdgcn_rcpf(1.0f + __builtin_amdgcn_exp2f(v0.w * 1.4426950408889634f));
;                         c1.x = __builtin_amdgcn_rcpf(1.0f + __builtin_amdgcn_exp2f(v1.x * 1.4426950408889634f)); c1.y = __builtin_amdgcn_rcpf(1.0f + __builtin_amdgcn_exp2f(v1.y * 1.4426950408889634f));
;                         c1.z = __builtin_amdgcn_rcpf(1.0f + __builtin_amdgcn_exp2f(v1.z * 1.4426950408889634f)); c1.w = __builtin_amdgcn_rcpf(1.0f + __builtin_amdgcn_exp2f(v1.w * 1.4426950408889634f));
;                         w.x = pkh2(c0.x, c0.y); w.y = pkh2(c0.z, c0.w); w.z = pkh2(c1.x, c1.y); w.w = pkh2(c1.z, c1.w);
;                         unsigned short* dst = (type == 1 ? Ff : Fb) + (size_t)row * D + (c - type * 1024);
;                         *(u32x4*)dst = w;
.LBB0_505:
	s_lshl_b32 s16, s17, 10
	s_andn2_b64 vcc, exec, s[6:7]
	v_lshlrev_b64 v[40:41], 11, v[40:41]
	s_cbranch_vccnz .LBB0_507
	s_mov_b32 s100, 0x3fb8aa3b
	v_pk_mul_f32 v[10:11], v[44:45], s[100:101] op_sel_hi:[1,0]
	v_pk_mul_f32 v[12:13], v[42:43], s[100:101] op_sel_hi:[1,0]
	v_mul_f32_e32 v35, 0x3fb8aa3b, v38
	v_mul_f32_e32 v37, 0x3fb8aa3b, v39
	v_pk_mul_f32 v[16:17], v[16:17], s[100:101] op_sel_hi:[1,0]
	v_exp_f32_e32 v10, v10
	v_exp_f32_e32 v11, v11
	v_exp_f32_e32 v12, v12
	v_exp_f32_e32 v13, v13
	v_exp_f32_e32 v35, v35
	v_exp_f32_e32 v37, v37
	v_exp_f32_e32 v16, v16
	v_exp_f32_e32 v17, v17
	v_pk_add_f32 v[10:11], v[10:11], 1.0 op_sel_hi:[1,0]
	v_pk_add_f32 v[12:13], v[12:13], 1.0 op_sel_hi:[1,0]
	v_add_f32_e32 v35, 1.0, v35
	v_add_f32_e32 v37, 1.0, v37
	v_pk_add_f32 v[16:17], v[16:17], 1.0 op_sel_hi:[1,0]
	v_rcp_f32_e32 v10, v10
	v_rcp_f32_e32 v11, v11
	v_rcp_f32_e32 v12, v12
	v_rcp_f32_e32 v13, v13
	v_rcp_f32_e32 v35, v35
	v_rcp_f32_e32 v37, v37
	v_rcp_f32_e32 v16, v16
	v_rcp_f32_e32 v17, v17
	v_cvt_f16_f32_e32 v10, v10
	v_cvt_f16_f32_sdwa v11, v11 dst_sel:WORD_1 dst_unused:UNUSED_PAD src0_sel:DWORD
	v_cvt_f16_f32_e32 v12, v12
	v_cvt_f16_f32_sdwa v13, v13 dst_sel:WORD_1 dst_unused:UNUSED_PAD src0_sel:DWORD
	v_cvt_f16_f32_e32 v35, v35
	v_cvt_f16_f32_sdwa v37, v37 dst_sel:WORD_1 dst_unused:UNUSED_PAD src0_sel:DWORD
	v_cvt_f16_f32_e32 v16, v16
	v_cvt_f16_f32_sdwa v17, v17 dst_sel:WORD_1 dst_unused:UNUSED_PAD src0_sel:DWORD
	s_and_b64 s[6:7], s[2:3], exec
	s_cselect_b32 s7, s61, s23
	s_cselect_b32 s6, s60, s22
	v_or_b32_e32 v10, v11, v10
	v_or_b32_e32 v11, v13, v12
	v_or_b32_e32 v12, v37, v35
	v_or_b32_e32 v13, v17, v16
	v_lshl_add_u64 v[48:49], s[6:7], 0, v[40:41]
	v_subrev_u32_e32 v50, s16, v34

; __device__ __forceinline__ unsigned pkh2(float lo, float hi) { _Float16 a = (_Float16)lo, b = (_Float16)hi; return (unsigned)__builtin_bit_cast(unsigned short, a) | ((unsigned)__builtin_bit_cast(unsigned short, b) << 16); }
;     template <int NA, int NM> __device__ __forceinline__ void operator()(const f32x4 (&acc)[NA][2][NM][2], const pg8::Unit& u, int ro, int wr, int wc, int fr, int fq) const {
;     ...
;                         c0.x = __builtin_amdgcn_rcpf(1.0f + __builtin_amdgcn_exp2f(v0.x * 1.4426950408889634f)); c0.y = __builtin_amdgcn_rcpf(1.0f + __builtin_amdgcn_exp2f(v0.y * 1.4426950408889634f));
;                         c0.z = __builtin_amdgcn_rcpf(1.0f + __builtin_amdgcn_exp2f(v0.z * 1.4426950408889634f)); c0.w = __builtin_amdgcn_rcpf(1.0f + __builtin_amdgcn_exp2f(v0.w * 1.4426950408889634f));
;                         c1.x = __builtin_amdgcn_rcpf(1.0f + __builtin_amdgcn_exp2f(v1.x * 1.4426950408889634f)); c1.y = __builtin_amdgcn_rcpf(1.0f + __builtin_amdgcn_exp2f(v1.y * 1.4426950408889634f));
;                         c1.z = __builtin_amdgcn_rcpf(1.0f + __builtin_amdgcn_exp2f(v1.z * 1.4426950408889634f)); c1.w = __builtin_amdgcn_rcpf(1.0f + __builtin_amdgcn_exp2f(v1.w * 1.4426950408889634f));
;                         w.x = pkh2(c0.x, c0.y); w.y = pkh2(c0.z, c0.w); w.z = pkh2(c1.x, c1.y); w.w = pkh2(c1.z, c1.w);
;                         unsigned short* dst = (type == 1 ? Ff : Fb) + (size_t)row * D + (c - type * 1024);
;                         *(u32x4*)dst = w;
.LBB0_509:
	s_andn2_b64 vcc, exec, s[4:5]
	s_cbranch_vccnz .LBB0_490
	s_mov_b32 s100, 0x3fb8aa3b
	v_pk_mul_f32 v[2:3], v[12:13], s[100:101] op_sel_hi:[1,0]
	v_pk_mul_f32 v[4:5], v[10:11], s[100:101] op_sel_hi:[1,0]
	v_pk_mul_f32 v[8:9], v[8:9], s[100:101] op_sel_hi:[1,0]
	v_pk_mul_f32 v[6:7], v[6:7], s[100:101] op_sel_hi:[1,0]
	v_exp_f32_e32 v2, v2
	v_exp_f32_e32 v3, v3
	v_exp_f32_e32 v4, v4
	v_exp_f32_e32 v5, v5
	v_exp_f32_e32 v8, v8
	v_exp_f32_e32 v9, v9
	v_exp_f32_e32 v6, v6
	v_exp_f32_e32 v7, v7
	v_pk_add_f32 v[2:3], v[2:3], 1.0 op_sel_hi:[1,0]
	v_pk_add_f32 v[4:5], v[4:5], 1.0 op_sel_hi:[1,0]
	v_pk_add_f32 v[8:9], v[8:9], 1.0 op_sel_hi:[1,0]
	v_pk_add_f32 v[6:7], v[6:7], 1.0 op_sel_hi:[1,0]
	v_rcp_f32_e32 v2, v2
	v_rcp_f32_e32 v3, v3
	v_rcp_f32_e32 v4, v4
	v_rcp_f32_e32 v5, v5
	v_rcp_f32_e32 v8, v8
	v_rcp_f32_e32 v9, v9
	v_rcp_f32_e32 v6, v6
	v_rcp_f32_e32 v7, v7
	v_cvt_f16_f32_e32 v2, v2
	v_cvt_f16_f32_sdwa v3, v3 dst_sel:WORD_1 dst_unused:UNUSED_PAD src0_sel:DWORD
	v_cvt_f16_f32_e32 v4, v4
	v_cvt_f16_f32_sdwa v5, v5 dst_sel:WORD_1 dst_unused:UNUSED_PAD src0_sel:DWORD
	v_cvt_f16_f32_e32 v8, v8
	v_cvt_f16_f32_sdwa v9, v9 dst_sel:WORD_1 dst_unused:UNUSED_PAD src0_sel:DWORD
	v_cvt_f16_f32_e32 v6, v6
	v_cvt_f16_f32_sdwa v7, v7 dst_sel:WORD_1 dst_unused:UNUSED_PAD src0_sel:DWORD
	s_and_b64 s[0:1], s[2:3], exec
	s_cselect_b32 s1, s61, s23
	s_cselect_b32 s0, s60, s22
	v_or_b32_e32 v2, v3, v2
	v_or_b32_e32 v3, v5, v4
	v_or_b32_e32 v4, v9, v8
	v_or_b32_e32 v5, v7, v6
	v_lshl_add_u64 v[14:15], s[0:1], 0, v[40:41]
	v_subrev_u32_e32 v16, s16, v17
	s_branch .LBB0_490
